# v45 + s_sleep removed from the grid-barrier spin loops (polls back to back; each poll already waits a full round trip)
# speedup vs baseline: 1.0083x; 1.0083x over previous
; __device__ __forceinline__ unsigned xb_ld(unsigned* p)              { return __hip_atomic_load(p, __ATOMIC_RELAXED, __HIP_MEMORY_SCOPE_AGENT); }
; __device__ __forceinline__ void xcd_barrier_complete(unsigned* bar, unsigned x, unsigned& nloc, unsigned& nx) {
;     ...
;     for (;;) {
;         sum = 0u; cnt = 0u; mine = 0u;
; #pragma unroll
;         for (unsigned j = 0; j < 16; ++j) { const unsigned c = xb_ld(&bar[XB_XCNT(j)]); sum += c; cnt += (c > 0u) ? 1u : 0u; mine = (j == x) ? c : mine; }
;         if (sum == G) break;
;         __builtin_amdgcn_s_sleep(1);
;         if ((++sp & 255u) == 0u) { if (xb_ld(&bar[XB_TMO])) break; if (sp > XB_SPIN_CAP) { atomicAdd(&bar[XB_TMO], 1u); break; } }
;     }
.LBB0_555:
	v_readlane_b32 s6, v254, 25
	v_readlane_b32 s7, v254, 26
	global_load_dword v14, v0, s[38:39] offset:1024 sc1
	global_load_dword v1, v0, s[38:39] offset:1280 sc1
	s_waitcnt lgkmcnt(0)
	global_load_dword v2, v0, s[38:39] offset:1536 sc1
	global_load_dword v3, v0, s[38:39] offset:1792 sc1
	global_load_dword v4, v0, s[38:39] offset:2048 sc1
	global_load_dword v5, v0, s[38:39] offset:2304 sc1
	global_load_dword v6, v0, s[38:39] offset:2560 sc1
	global_load_dword v7, v0, s[38:39] offset:2816 sc1
	global_load_dword v8, v0, s[38:39] offset:3072 sc1
	global_load_dword v9, v0, s[38:39] offset:3328 sc1
	global_load_dword v10, v0, s[38:39] offset:3584 sc1
	global_load_dword v11, v0, s[38:39] offset:3840 sc1
	global_load_dword v12, v0, s[30:31] sc1
	global_load_dword v13, v0, s[28:29] sc1
	global_load_dword v15, v0, s[6:7] sc1
	v_readlane_b32 s6, v254, 27
	v_readlane_b32 s7, v254, 28
	s_mov_b64 s[8:9], -1
	s_waitcnt vmcnt(13)
	v_add_u32_e32 v17, v1, v14
	s_nop 1
	global_load_dword v16, v0, s[6:7] sc1
	s_waitcnt vmcnt(13)
	v_add_u32_e32 v17, v17, v2
	s_waitcnt vmcnt(12)
	v_add_u32_e32 v17, v17, v3
	s_waitcnt vmcnt(11)
	v_add_u32_e32 v17, v17, v4
	s_waitcnt vmcnt(10)
	v_add_u32_e32 v17, v17, v5
	s_waitcnt vmcnt(9)
	v_add_u32_e32 v17, v17, v6
	s_waitcnt vmcnt(8)
	v_add_u32_e32 v17, v17, v7
	s_waitcnt vmcnt(7)
	v_add_u32_e32 v17, v17, v8
	s_waitcnt vmcnt(6)
	v_add_u32_e32 v17, v17, v9
	s_waitcnt vmcnt(5)
	v_add_u32_e32 v17, v17, v10
	s_waitcnt vmcnt(4)
	v_add_u32_e32 v17, v17, v11
	s_waitcnt vmcnt(3)
	v_add_u32_e32 v17, v17, v12
	s_waitcnt vmcnt(2)
	v_add_u32_e32 v17, v17, v13
	s_waitcnt vmcnt(1)
	v_add_u32_e32 v17, v17, v15
	s_mov_b64 s[6:7], -1
	s_waitcnt vmcnt(0)
	v_add_u32_e32 v17, v17, v16
	v_cmp_eq_u32_e32 vcc, s79, v17
	s_cbranch_vccnz .LBB0_554
	s_and_b32 s3, s1, 0xff
	s_cmp_eq_u32 s3, 0
	s_mov_b64 s[12:13], -1
	s_nop 0
	s_cbranch_scc1 .LBB0_559
	s_and_b64 vcc, exec, s[12:13]
	s_cbranch_vccz .LBB0_554

.LBB0_573:
	s_and_b32 s1, s0, 0xff
	s_mov_b64 s[20:21], -1
	s_cmp_lg_u32 s1, 0
	s_mov_b64 s[24:25], -1
	s_nop 0
	s_cbranch_scc0 .LBB0_576
	s_and_b64 vcc, exec, s[24:25]
	s_cbranch_vccz .LBB0_572

.LBB0_590:
	s_and_b32 s1, s0, 0xff
	s_mov_b64 s[18:19], -1
	s_cmp_lg_u32 s1, 0
	s_mov_b64 s[22:23], -1
	s_nop 0
	s_cbranch_scc0 .LBB0_593
	s_and_b64 vcc, exec, s[22:23]
	s_cbranch_vccz .LBB0_589

; __device__ __forceinline__ unsigned xb_ld(unsigned* p)              { return __hip_atomic_load(p, __ATOMIC_RELAXED, __HIP_MEMORY_SCOPE_AGENT); }
; __device__ __forceinline__ void xcd_barrier_complete(unsigned* bar, unsigned x, unsigned& nloc, unsigned& nx) {
;     ...
;     for (;;) {
;         sum = 0u; cnt = 0u; mine = 0u;
; #pragma unroll
;         for (unsigned j = 0; j < 16; ++j) { const unsigned c = xb_ld(&bar[XB_XCNT(j)]); sum += c; cnt += (c > 0u) ? 1u : 0u; mine = (j == x) ? c : mine; }
;         if (sum == G) break;
;         __builtin_amdgcn_s_sleep(1);
;         if ((++sp & 255u) == 0u) { if (xb_ld(&bar[XB_TMO])) break; if (sp > XB_SPIN_CAP) { atomicAdd(&bar[XB_TMO], 1u); break; } }
;     }
.LBB0_616:
	v_readlane_b32 s6, v254, 25
	v_readlane_b32 s7, v254, 26
	global_load_dword v14, v0, s[38:39] offset:1024 sc1
	global_load_dword v1, v0, s[38:39] offset:1280 sc1
	s_waitcnt lgkmcnt(0)
	global_load_dword v2, v0, s[38:39] offset:1536 sc1
	global_load_dword v3, v0, s[38:39] offset:1792 sc1
	global_load_dword v4, v0, s[38:39] offset:2048 sc1
	global_load_dword v5, v0, s[38:39] offset:2304 sc1
	global_load_dword v6, v0, s[38:39] offset:2560 sc1
	global_load_dword v7, v0, s[38:39] offset:2816 sc1
	global_load_dword v8, v0, s[38:39] offset:3072 sc1
	global_load_dword v9, v0, s[38:39] offset:3328 sc1
	global_load_dword v10, v0, s[38:39] offset:3584 sc1
	global_load_dword v11, v0, s[38:39] offset:3840 sc1
	global_load_dword v12, v0, s[30:31] sc1
	global_load_dword v13, v0, s[28:29] sc1
	global_load_dword v15, v0, s[6:7] sc1
	v_readlane_b32 s6, v254, 27
	v_readlane_b32 s7, v254, 28
	s_mov_b64 s[12:13], -1
	s_waitcnt vmcnt(13)
	v_add_u32_e32 v17, v1, v14
	s_nop 1
	global_load_dword v16, v0, s[6:7] sc1
	s_waitcnt vmcnt(13)
	v_add_u32_e32 v17, v17, v2
	s_waitcnt vmcnt(12)
	v_add_u32_e32 v17, v17, v3
	s_waitcnt vmcnt(11)
	v_add_u32_e32 v17, v17, v4
	s_waitcnt vmcnt(10)
	v_add_u32_e32 v17, v17, v5
	s_waitcnt vmcnt(9)
	v_add_u32_e32 v17, v17, v6
	s_waitcnt vmcnt(8)
	v_add_u32_e32 v17, v17, v7
	s_waitcnt vmcnt(7)
	v_add_u32_e32 v17, v17, v8
	s_waitcnt vmcnt(6)
	v_add_u32_e32 v17, v17, v9
	s_waitcnt vmcnt(5)
	v_add_u32_e32 v17, v17, v10
	s_waitcnt vmcnt(4)
	v_add_u32_e32 v17, v17, v11
	s_waitcnt vmcnt(3)
	v_add_u32_e32 v17, v17, v12
	s_waitcnt vmcnt(2)
	v_add_u32_e32 v17, v17, v13
	s_waitcnt vmcnt(1)
	v_add_u32_e32 v17, v17, v15
	s_mov_b64 s[6:7], -1
	s_waitcnt vmcnt(0)
	v_add_u32_e32 v17, v17, v16
	v_cmp_eq_u32_e32 vcc, s79, v17
	s_cbranch_vccnz .LBB0_615
	s_and_b32 s3, s1, 0xff
	s_cmp_eq_u32 s3, 0
	s_mov_b64 s[14:15], -1
	s_nop 0
	s_cbranch_scc1 .LBB0_620
	s_and_b64 vcc, exec, s[14:15]
	s_cbranch_vccz .LBB0_615

.LBB0_634:
	s_and_b32 s1, s0, 0xff
	s_mov_b64 s[22:23], -1
	s_cmp_lg_u32 s1, 0
	s_mov_b64 s[26:27], -1
	s_nop 0
	s_cbranch_scc0 .LBB0_637
	s_and_b64 vcc, exec, s[26:27]
	s_cbranch_vccz .LBB0_633

; __device__ __forceinline__ unsigned xb_ld(unsigned* p)              { return __hip_atomic_load(p, __ATOMIC_RELAXED, __HIP_MEMORY_SCOPE_AGENT); }
; __device__ __forceinline__ void xcd_barrier_complete(unsigned* bar, unsigned x, unsigned& nloc, unsigned& nx) {
;     ...
;     for (;;) {
;         sum = 0u; cnt = 0u; mine = 0u;
; #pragma unroll
;         for (unsigned j = 0; j < 16; ++j) { const unsigned c = xb_ld(&bar[XB_XCNT(j)]); sum += c; cnt += (c > 0u) ? 1u : 0u; mine = (j == x) ? c : mine; }
;         if (sum == G) break;
;         __builtin_amdgcn_s_sleep(1);
;         if ((++sp & 255u) == 0u) { if (xb_ld(&bar[XB_TMO])) break; if (sp > XB_SPIN_CAP) { atomicAdd(&bar[XB_TMO], 1u); break; } }
;     }
.LBB0_814:
	v_readlane_b32 s8, v254, 25
	v_readlane_b32 s9, v254, 26
	global_load_dword v14, v0, s[38:39] offset:1024 sc1
	global_load_dword v1, v0, s[38:39] offset:1280 sc1
	s_waitcnt lgkmcnt(0)
	global_load_dword v2, v0, s[38:39] offset:1536 sc1
	global_load_dword v3, v0, s[38:39] offset:1792 sc1
	global_load_dword v4, v0, s[38:39] offset:2048 sc1
	global_load_dword v5, v0, s[38:39] offset:2304 sc1
	global_load_dword v6, v0, s[38:39] offset:2560 sc1
	global_load_dword v7, v0, s[38:39] offset:2816 sc1
	global_load_dword v8, v0, s[38:39] offset:3072 sc1
	global_load_dword v9, v0, s[38:39] offset:3328 sc1
	global_load_dword v10, v0, s[38:39] offset:3584 sc1
	global_load_dword v11, v0, s[38:39] offset:3840 sc1
	global_load_dword v12, v0, s[30:31] sc1
	global_load_dword v13, v0, s[28:29] sc1
	global_load_dword v15, v0, s[8:9] sc1
	v_readlane_b32 s8, v254, 27
	v_readlane_b32 s9, v254, 28
	s_mov_b64 s[12:13], -1
	s_waitcnt vmcnt(13)
	v_add_u32_e32 v17, v1, v14
	s_nop 1
	global_load_dword v16, v0, s[8:9] sc1
	s_waitcnt vmcnt(13)
	v_add_u32_e32 v17, v17, v2
	s_waitcnt vmcnt(12)
	v_add_u32_e32 v17, v17, v3
	s_waitcnt vmcnt(11)
	v_add_u32_e32 v17, v17, v4
	s_waitcnt vmcnt(10)
	v_add_u32_e32 v17, v17, v5
	s_waitcnt vmcnt(9)
	v_add_u32_e32 v17, v17, v6
	s_waitcnt vmcnt(8)
	v_add_u32_e32 v17, v17, v7
	s_waitcnt vmcnt(7)
	v_add_u32_e32 v17, v17, v8
	s_waitcnt vmcnt(6)
	v_add_u32_e32 v17, v17, v9
	s_waitcnt vmcnt(5)
	v_add_u32_e32 v17, v17, v10
	s_waitcnt vmcnt(4)
	v_add_u32_e32 v17, v17, v11
	s_waitcnt vmcnt(3)
	v_add_u32_e32 v17, v17, v12
	s_waitcnt vmcnt(2)
	v_add_u32_e32 v17, v17, v13
	s_waitcnt vmcnt(1)
	v_add_u32_e32 v17, v17, v15
	s_mov_b64 s[8:9], -1
	s_waitcnt vmcnt(0)
	v_add_u32_e32 v17, v17, v16
	v_cmp_eq_u32_e32 vcc, s79, v17
	s_cbranch_vccnz .LBB0_813
	s_and_b32 s3, s1, 0xff
	s_cmp_eq_u32 s3, 0
	s_mov_b64 s[14:15], -1
	s_nop 0
	s_cbranch_scc1 .LBB0_818
	s_and_b64 vcc, exec, s[14:15]
	s_cbranch_vccz .LBB0_813

; __device__ __forceinline__ unsigned xb_ld(unsigned* p)              { return __hip_atomic_load(p, __ATOMIC_RELAXED, __HIP_MEMORY_SCOPE_AGENT); }
; __device__ __forceinline__ void xcd_barrier_complete(unsigned* bar, unsigned x, unsigned& nloc, unsigned& nx) {
;     ...
;     for (;;) {
;         sum = 0u; cnt = 0u; mine = 0u;
; #pragma unroll
;         for (unsigned j = 0; j < 16; ++j) { const unsigned c = xb_ld(&bar[XB_XCNT(j)]); sum += c; cnt += (c > 0u) ? 1u : 0u; mine = (j == x) ? c : mine; }
;         if (sum == G) break;
;         __builtin_amdgcn_s_sleep(1);
;         if ((++sp & 255u) == 0u) { if (xb_ld(&bar[XB_TMO])) break; if (sp > XB_SPIN_CAP) { atomicAdd(&bar[XB_TMO], 1u); break; } }
;     }
.LBB0_1120:
	v_readlane_b32 s6, v255, 26
	v_readlane_b32 s7, v255, 27
	global_load_dword v12, v0, s[38:39] offset:1024 sc1
	global_load_dword v1, v0, s[38:39] offset:1280 sc1
	s_waitcnt lgkmcnt(0)
	global_load_dword v2, v0, s[38:39] offset:1536 sc1
	global_load_dword v3, v0, s[38:39] offset:1792 sc1
	global_load_dword v4, v0, s[38:39] offset:2048 sc1
	global_load_dword v5, v0, s[38:39] offset:2304 sc1
	global_load_dword v6, v0, s[38:39] offset:2560 sc1
	global_load_dword v7, v0, s[38:39] offset:2816 sc1
	global_load_dword v8, v0, s[38:39] offset:3072 sc1
	global_load_dword v9, v0, s[38:39] offset:3328 sc1
	global_load_dword v10, v0, s[38:39] offset:3584 sc1
	global_load_dword v11, v0, s[38:39] offset:3840 sc1
	global_load_dword v13, v0, s[6:7] sc1
	v_readlane_b32 s6, v255, 28
	v_readlane_b32 s7, v255, 29
	s_mov_b64 s[8:9], -1
	s_waitcnt vmcnt(11)
	v_add_u32_e32 v17, v1, v12
	s_nop 1
	global_load_dword v14, v0, s[6:7] sc1
	v_readlane_b32 s6, v254, 25
	v_readlane_b32 s7, v254, 26
	s_waitcnt vmcnt(11)
	v_add_u32_e32 v17, v17, v2
	s_waitcnt vmcnt(10)
	v_add_u32_e32 v17, v17, v3
	s_waitcnt vmcnt(9)
	v_add_u32_e32 v17, v17, v4
	s_waitcnt vmcnt(8)
	v_add_u32_e32 v17, v17, v5
	s_waitcnt vmcnt(7)
	v_add_u32_e32 v17, v17, v6
	global_load_dword v15, v0, s[6:7] sc1
	v_readlane_b32 s6, v254, 27
	v_readlane_b32 s7, v254, 28
	s_waitcnt vmcnt(7)
	v_add_u32_e32 v17, v17, v7
	s_waitcnt vmcnt(6)
	v_add_u32_e32 v17, v17, v8
	s_waitcnt vmcnt(5)
	v_add_u32_e32 v17, v17, v9
	s_waitcnt vmcnt(4)
	v_add_u32_e32 v17, v17, v10
	s_waitcnt vmcnt(3)
	v_add_u32_e32 v17, v17, v11
	global_load_dword v16, v0, s[6:7] sc1
	s_waitcnt vmcnt(3)
	v_add_u32_e32 v17, v17, v13
	s_mov_b64 s[6:7], -1
	s_waitcnt vmcnt(2)
	v_add_u32_e32 v17, v17, v14
	s_waitcnt vmcnt(1)
	v_add_u32_e32 v17, v17, v15
	s_waitcnt vmcnt(0)
	v_add_u32_e32 v17, v17, v16
	v_cmp_eq_u32_e32 vcc, s79, v17
	s_cbranch_vccnz .LBB0_1119
	s_and_b32 s3, s1, 0xff
	s_cmp_eq_u32 s3, 0
	s_mov_b64 s[10:11], -1
	s_nop 0
	s_cbranch_scc1 .LBB0_1124
	s_and_b64 vcc, exec, s[10:11]
	s_cbranch_vccz .LBB0_1119

.LBB0_1138:
	s_and_b32 s1, s0, 0xff
	s_mov_b64 s[44:45], -1
	s_cmp_lg_u32 s1, 0
	s_mov_b64 s[86:87], -1
	s_nop 0
	s_cbranch_scc0 .LBB0_1141
	s_and_b64 vcc, exec, s[86:87]
	s_cbranch_vccz .LBB0_1137

.LBB0_1155:
	s_and_b32 s1, s0, 0xff
	s_mov_b64 s[34:35], -1
	s_cmp_lg_u32 s1, 0
	s_mov_b64 s[68:69], -1
	s_nop 0
	s_cbranch_scc0 .LBB0_1158
	s_and_b64 vcc, exec, s[68:69]
	s_cbranch_vccz .LBB0_1154

; __device__ __forceinline__ unsigned xb_ld(unsigned* p)              { return __hip_atomic_load(p, __ATOMIC_RELAXED, __HIP_MEMORY_SCOPE_AGENT); }
; __device__ __forceinline__ void xcd_barrier_complete(unsigned* bar, unsigned x, unsigned& nloc, unsigned& nx) {
;     ...
;     for (;;) {
;         sum = 0u; cnt = 0u; mine = 0u;
; #pragma unroll
;         for (unsigned j = 0; j < 16; ++j) { const unsigned c = xb_ld(&bar[XB_XCNT(j)]); sum += c; cnt += (c > 0u) ? 1u : 0u; mine = (j == x) ? c : mine; }
;         if (sum == G) break;
;         __builtin_amdgcn_s_sleep(1);
;         if ((++sp & 255u) == 0u) { if (xb_ld(&bar[XB_TMO])) break; if (sp > XB_SPIN_CAP) { atomicAdd(&bar[XB_TMO], 1u); break; } }
;     }
.LBB0_1257:
	v_readlane_b32 s6, v254, 25
	v_readlane_b32 s7, v254, 26
	global_load_dword v14, v0, s[38:39] offset:1024 sc1
	global_load_dword v1, v0, s[38:39] offset:1280 sc1
	s_waitcnt lgkmcnt(0)
	global_load_dword v2, v0, s[38:39] offset:1536 sc1
	global_load_dword v3, v0, s[38:39] offset:1792 sc1
	global_load_dword v4, v0, s[38:39] offset:2048 sc1
	global_load_dword v5, v0, s[38:39] offset:2304 sc1
	global_load_dword v6, v0, s[38:39] offset:2560 sc1
	global_load_dword v7, v0, s[38:39] offset:2816 sc1
	global_load_dword v8, v0, s[38:39] offset:3072 sc1
	global_load_dword v9, v0, s[38:39] offset:3328 sc1
	global_load_dword v10, v0, s[38:39] offset:3584 sc1
	global_load_dword v11, v0, s[38:39] offset:3840 sc1
	global_load_dword v12, v0, s[30:31] sc1
	global_load_dword v13, v0, s[28:29] sc1
	global_load_dword v15, v0, s[6:7] sc1
	v_readlane_b32 s6, v254, 27
	v_readlane_b32 s7, v254, 28
	s_mov_b64 s[8:9], -1
	s_waitcnt vmcnt(13)
	v_add_u32_e32 v17, v1, v14
	s_nop 1
	global_load_dword v16, v0, s[6:7] sc1
	s_waitcnt vmcnt(13)
	v_add_u32_e32 v17, v17, v2
	s_waitcnt vmcnt(12)
	v_add_u32_e32 v17, v17, v3
	s_waitcnt vmcnt(11)
	v_add_u32_e32 v17, v17, v4
	s_waitcnt vmcnt(10)
	v_add_u32_e32 v17, v17, v5
	s_waitcnt vmcnt(9)
	v_add_u32_e32 v17, v17, v6
	s_waitcnt vmcnt(8)
	v_add_u32_e32 v17, v17, v7
	s_waitcnt vmcnt(7)
	v_add_u32_e32 v17, v17, v8
	s_waitcnt vmcnt(6)
	v_add_u32_e32 v17, v17, v9
	s_waitcnt vmcnt(5)
	v_add_u32_e32 v17, v17, v10
	s_waitcnt vmcnt(4)
	v_add_u32_e32 v17, v17, v11
	s_waitcnt vmcnt(3)
	v_add_u32_e32 v17, v17, v12
	s_waitcnt vmcnt(2)
	v_add_u32_e32 v17, v17, v13
	s_waitcnt vmcnt(1)
	v_add_u32_e32 v17, v17, v15
	s_mov_b64 s[6:7], -1
	s_waitcnt vmcnt(0)
	v_add_u32_e32 v17, v17, v16
	v_cmp_eq_u32_e32 vcc, s79, v17
	s_cbranch_vccnz .LBB0_1256
	s_and_b32 s3, s1, 0xff
	s_cmp_eq_u32 s3, 0
	s_mov_b64 s[10:11], -1
	s_nop 0
	s_cbranch_scc1 .LBB0_1261
	s_and_b64 vcc, exec, s[10:11]
	s_cbranch_vccz .LBB0_1256

.LBB0_1292:
	s_and_b32 s1, s0, 0xff
	s_mov_b64 s[16:17], -1
	s_cmp_lg_u32 s1, 0
	s_mov_b64 s[20:21], -1
	s_nop 0
	s_cbranch_scc0 .LBB0_1295
	s_and_b64 vcc, exec, s[20:21]
	s_cbranch_vccz .LBB0_1291

; __device__ __forceinline__ unsigned xb_ld(unsigned* p)              { return __hip_atomic_load(p, __ATOMIC_RELAXED, __HIP_MEMORY_SCOPE_AGENT); }
; __device__ __forceinline__ void xcd_barrier_complete(unsigned* bar, unsigned x, unsigned& nloc, unsigned& nx) {
;     ...
;     for (;;) {
;         sum = 0u; cnt = 0u; mine = 0u;
; #pragma unroll
;         for (unsigned j = 0; j < 16; ++j) { const unsigned c = xb_ld(&bar[XB_XCNT(j)]); sum += c; cnt += (c > 0u) ? 1u : 0u; mine = (j == x) ? c : mine; }
;         if (sum == G) break;
;         __builtin_amdgcn_s_sleep(1);
;         if ((++sp & 255u) == 0u) { if (xb_ld(&bar[XB_TMO])) break; if (sp > XB_SPIN_CAP) { atomicAdd(&bar[XB_TMO], 1u); break; } }
;     }
.LBB0_2064:
	v_readlane_b32 s4, v254, 25
	v_readlane_b32 s5, v254, 26
	global_load_dword v14, v0, s[38:39] offset:1024 sc1
	global_load_dword v1, v0, s[38:39] offset:1280 sc1
	s_waitcnt lgkmcnt(0)
	global_load_dword v2, v0, s[38:39] offset:1536 sc1
	global_load_dword v3, v0, s[38:39] offset:1792 sc1
	global_load_dword v4, v0, s[38:39] offset:2048 sc1
	global_load_dword v5, v0, s[38:39] offset:2304 sc1
	global_load_dword v6, v0, s[38:39] offset:2560 sc1
	global_load_dword v7, v0, s[38:39] offset:2816 sc1
	global_load_dword v8, v0, s[38:39] offset:3072 sc1
	global_load_dword v9, v0, s[38:39] offset:3328 sc1
	global_load_dword v10, v0, s[38:39] offset:3584 sc1
	global_load_dword v11, v0, s[38:39] offset:3840 sc1
	global_load_dword v12, v0, s[30:31] sc1
	global_load_dword v13, v0, s[28:29] sc1
	global_load_dword v15, v0, s[4:5] sc1
	v_readlane_b32 s4, v254, 27
	v_readlane_b32 s5, v254, 28
	s_mov_b64 s[6:7], -1
	s_waitcnt vmcnt(13)
	v_add_u32_e32 v17, v1, v14
	s_nop 1
	global_load_dword v16, v0, s[4:5] sc1
	s_waitcnt vmcnt(13)
	v_add_u32_e32 v17, v17, v2
	s_waitcnt vmcnt(12)
	v_add_u32_e32 v17, v17, v3
	s_waitcnt vmcnt(11)
	v_add_u32_e32 v17, v17, v4
	s_waitcnt vmcnt(10)
	v_add_u32_e32 v17, v17, v5
	s_waitcnt vmcnt(9)
	v_add_u32_e32 v17, v17, v6
	s_waitcnt vmcnt(8)
	v_add_u32_e32 v17, v17, v7
	s_waitcnt vmcnt(7)
	v_add_u32_e32 v17, v17, v8
	s_waitcnt vmcnt(6)
	v_add_u32_e32 v17, v17, v9
	s_waitcnt vmcnt(5)
	v_add_u32_e32 v17, v17, v10
	s_waitcnt vmcnt(4)
	v_add_u32_e32 v17, v17, v11
	s_waitcnt vmcnt(3)
	v_add_u32_e32 v17, v17, v12
	s_waitcnt vmcnt(2)
	v_add_u32_e32 v17, v17, v13
	s_waitcnt vmcnt(1)
	v_add_u32_e32 v17, v17, v15
	s_mov_b64 s[4:5], -1
	s_waitcnt vmcnt(0)
	v_add_u32_e32 v17, v17, v16
	v_cmp_eq_u32_e32 vcc, s79, v17
	s_cbranch_vccnz .LBB0_2063
	s_and_b32 s4, s10, 0xff
	s_cmp_eq_u32 s4, 0
	s_mov_b64 s[4:5], -1
	s_mov_b64 s[8:9], -1
	s_nop 0
	s_cbranch_scc1 .LBB0_2068
	s_and_b64 vcc, exec, s[8:9]
	s_cbranch_vccz .LBB0_2063

.LBB0_2082:
	s_and_b32 s18, s3, 0xff
	s_mov_b64 s[16:17], -1
	s_cmp_lg_u32 s18, 0
	s_mov_b64 s[20:21], -1
	s_nop 0
	s_cbranch_scc0 .LBB0_2085
	s_and_b64 vcc, exec, s[20:21]
	s_cbranch_vccz .LBB0_2081

.LBB0_2099:
	s_and_b32 s16, s3, 0xff
	s_mov_b64 s[14:15], -1
	s_cmp_lg_u32 s16, 0
	s_mov_b64 s[18:19], -1
	s_nop 0
	s_cbranch_scc0 .LBB0_2102
	s_and_b64 vcc, exec, s[18:19]
	s_cbranch_vccz .LBB0_2098

; __device__ __forceinline__ unsigned xb_ld(unsigned* p)              { return __hip_atomic_load(p, __ATOMIC_RELAXED, __HIP_MEMORY_SCOPE_AGENT); }
; __device__ __forceinline__ void xcd_barrier_complete(unsigned* bar, unsigned x, unsigned& nloc, unsigned& nx) {
;     ...
;     for (;;) {
;         sum = 0u; cnt = 0u; mine = 0u;
; #pragma unroll
;         for (unsigned j = 0; j < 16; ++j) { const unsigned c = xb_ld(&bar[XB_XCNT(j)]); sum += c; cnt += (c > 0u) ? 1u : 0u; mine = (j == x) ? c : mine; }
;         if (sum == G) break;
;         __builtin_amdgcn_s_sleep(1);
;         if ((++sp & 255u) == 0u) { if (xb_ld(&bar[XB_TMO])) break; if (sp > XB_SPIN_CAP) { atomicAdd(&bar[XB_TMO], 1u); break; } }
;     }
.LBB0_2166:
	v_readlane_b32 s6, v254, 25
	v_readlane_b32 s7, v254, 26
	global_load_dword v14, v0, s[38:39] offset:1024 sc1
	global_load_dword v1, v0, s[38:39] offset:1280 sc1
	s_waitcnt lgkmcnt(0)
	global_load_dword v2, v0, s[38:39] offset:1536 sc1
	global_load_dword v3, v0, s[38:39] offset:1792 sc1
	global_load_dword v4, v0, s[38:39] offset:2048 sc1
	global_load_dword v5, v0, s[38:39] offset:2304 sc1
	global_load_dword v6, v0, s[38:39] offset:2560 sc1
	global_load_dword v7, v0, s[38:39] offset:2816 sc1
	global_load_dword v8, v0, s[38:39] offset:3072 sc1
	global_load_dword v9, v0, s[38:39] offset:3328 sc1
	global_load_dword v10, v0, s[38:39] offset:3584 sc1
	global_load_dword v11, v0, s[38:39] offset:3840 sc1
	global_load_dword v12, v0, s[30:31] sc1
	global_load_dword v13, v0, s[28:29] sc1
	global_load_dword v15, v0, s[6:7] sc1
	v_readlane_b32 s6, v254, 27
	v_readlane_b32 s7, v254, 28
	s_mov_b64 s[8:9], -1
	s_waitcnt vmcnt(13)
	v_add_u32_e32 v17, v1, v14
	s_nop 1
	global_load_dword v16, v0, s[6:7] sc1
	s_waitcnt vmcnt(13)
	v_add_u32_e32 v17, v17, v2
	s_waitcnt vmcnt(12)
	v_add_u32_e32 v17, v17, v3
	s_waitcnt vmcnt(11)
	v_add_u32_e32 v17, v17, v4
	s_waitcnt vmcnt(10)
	v_add_u32_e32 v17, v17, v5
	s_waitcnt vmcnt(9)
	v_add_u32_e32 v17, v17, v6
	s_waitcnt vmcnt(8)
	v_add_u32_e32 v17, v17, v7
	s_waitcnt vmcnt(7)
	v_add_u32_e32 v17, v17, v8
	s_waitcnt vmcnt(6)
	v_add_u32_e32 v17, v17, v9
	s_waitcnt vmcnt(5)
	v_add_u32_e32 v17, v17, v10
	s_waitcnt vmcnt(4)
	v_add_u32_e32 v17, v17, v11
	s_waitcnt vmcnt(3)
	v_add_u32_e32 v17, v17, v12
	s_waitcnt vmcnt(2)
	v_add_u32_e32 v17, v17, v13
	s_waitcnt vmcnt(1)
	v_add_u32_e32 v17, v17, v15
	s_mov_b64 s[6:7], -1
	s_waitcnt vmcnt(0)
	v_add_u32_e32 v17, v17, v16
	v_cmp_eq_u32_e32 vcc, s79, v17
	s_cbranch_vccnz .LBB0_2165
	s_and_b32 s5, s4, 0xff
	s_cmp_eq_u32 s5, 0
	s_mov_b64 s[10:11], -1
	s_nop 0
	s_cbranch_scc1 .LBB0_2170
	s_and_b64 vcc, exec, s[10:11]
	s_cbranch_vccz .LBB0_2165

.LBB0_2184:
	s_and_b32 s4, s3, 0xff
	s_mov_b64 s[18:19], -1
	s_cmp_lg_u32 s4, 0
	s_mov_b64 s[22:23], -1
	s_nop 0
	s_cbranch_scc0 .LBB0_2187
	s_and_b64 vcc, exec, s[22:23]
	s_cbranch_vccz .LBB0_2183

.LBB0_2201:
	s_and_b32 s4, s3, 0xff
	s_mov_b64 s[16:17], -1
	s_cmp_lg_u32 s4, 0
	s_mov_b64 s[20:21], -1
	s_nop 0
	s_cbranch_scc0 .LBB0_2204
	s_and_b64 vcc, exec, s[20:21]
	s_cbranch_vccz .LBB0_2200
